# SwiGLU GEMM K-loop: LDS-DMA loads take SGPR base + lane offset (no 64-bit VALU adds), fragment read addresses hoisted out of the loop
# baseline (speedup 1.0000x reference)
; #define PG8_STAGE(bufoff, gbase, voff) do { _Pragma("unroll") for (int _i = 0; _i < 2; ++_i) \
;         __builtin_amdgcn_global_load_lds((const unsigned*)((const char*)(gbase) + (voff)[_i]), (PG8_LAS unsigned*)(lds + (bufoff) + ldsw + _i * 8192), 16, 0, 0); } while (0)
; #define PG8_LDA(dst, b, h) do { _Pragma("unroll") for (int m = 0; m < 4; ++m) _Pragma("unroll") for (int k = 0; k < 2; ++k) dst[m][k] = *(const PG8_LAS bf16x8*)(lds + PG8_SA(b, h) + aoff + m * 2048 + k * 1024); } while (0)
; #define PG8_LDB(dst, b, h) do { _Pragma("unroll") for (int n = 0; n < 2; ++n) _Pragma("unroll") for (int k = 0; k < 2; ++k) dst[n][k] = *(const PG8_LAS bf16x8*)(lds + PG8_SB(b, h) + boff + n * 2048 + k * 1024); } while (0)
; #define PG8_WAIT_V(n) asm volatile("s_waitcnt vmcnt(" #n ")" ::: "memory")
; #define PG8_WAIT_L(n) asm volatile("s_waitcnt lgkmcnt(" #n ")" ::: "memory")
; #define PG8_BAR __builtin_amdgcn_s_barrier()
; template <class Epi, class Sched, bool ALIGN_EPI = false, bool SP2 = false>
; __device__ __forceinline__ void gemm_phase(PG8_LAS unsigned char* lds, const Gemm g, const Sched& S, const Epi& E) {
;     ...
;     for (;;) {
;         const bool has_next = S.next(ui + 1, nxt);
;         const char* nA = has_next ? (const char*)g.A + (size_t)nxt.pm * tstep : cA; const char* nB = has_next ? (const char*)g.Bt + (size_t)nxt.pn * tstep : cB;
;         for (int t = 0; t < nt; t += 2) {
;             const bool last = (t == nt - 2);
;             const char* a1 = cA + (size_t)(t + 1) * kstep;
;             const char* a2 = last ? nA : cA + (size_t)(t + 2) * kstep; const char* b2 = last ? nB : cB + (size_t)(t + 2) * kstep;
;             const char* a3 = a2 + kstep; const char* b3 = b2 + kstep;
;             if (last && has_next) S.a_ready(nxt);
;             if constexpr (SP2) {
;             PG8_LDB(B0, 0, 0); PG8_LDB(B1, 0, 1); PG8_SCHED; PG8_LDA(At, 0, 0); PG8_STAGE(PG8_SA(1, 1), a1 + hstep, voffA);
;             PG8_WAIT_V(8); PG8_WAIT_L(0); PG8_BAR; PG8_MMA(0, 0, At, B0); PG8_MMA(0, 1, At, B1); PG8_BAR; PG8_SCHED;
;     ...
;         for (int a = 0; a < 2; ++a)
; #pragma unroll
;             for (int b = 0; b < 2; ++b)
; #pragma unroll
;                 for (int m = 0; m < 4; ++m)
; #pragma unroll
;                     for (int n = 0; n < 2; ++n) acc[a][b][m][n] = (f32x4){0.f, 0.f, 0.f, 0.f};
;         cur = nxt; cA = nA; cB = nB; ++ui;
.LBB0_1489:
	s_ashr_i32 s43, s42, 31
	s_lshl_b64 s[4:5], s[42:43], 19
	v_readlane_b32 s18, v252, 24
	v_readlane_b32 s19, v252, 25
	s_add_u32 s44, s18, s4
	s_addc_u32 s45, s19, s5
	s_and_b64 s[4:5], s[40:41], exec
	s_cselect_b32 s4, s45, s31
	s_cselect_b32 s5, s44, s30
	s_ashr_i32 s15, s14, 31
	s_lshl_b64 s[18:19], s[14:15], 19
	s_add_u32 s46, s50, s18
	s_addc_u32 s47, s51, s19
	s_and_b64 s[18:19], s[40:41], exec
	s_cselect_b32 s15, s47, s35
	s_cselect_b32 s18, s46, s34
	s_add_u32 s30, s30, 0x40080
	s_addc_u32 s31, s31, 0
	s_add_u32 s19, s34, 0x100
	v_mov_b32_e32 v2, 0
	s_addc_u32 s20, s35, 0
	s_mov_b32 s21, -2
	v_mov_b32_e32 v3, v2
	v_mov_b32_e32 v4, v2
	v_mov_b32_e32 v5, v2
	v_mov_b32_e32 v6, v2
	v_mov_b32_e32 v7, v2
	v_mov_b32_e32 v8, v2
	v_mov_b32_e32 v9, v2
	v_mov_b32_e32 v18, v2
	v_mov_b32_e32 v19, v2
	v_mov_b32_e32 v20, v2
	v_mov_b32_e32 v21, v2
	v_mov_b32_e32 v26, v2
	v_mov_b32_e32 v27, v2
	v_mov_b32_e32 v28, v2
	v_mov_b32_e32 v29, v2
	v_mov_b32_e32 v34, v2
	v_mov_b32_e32 v35, v2
	v_mov_b32_e32 v36, v2
	v_mov_b32_e32 v37, v2
	v_mov_b32_e32 v42, v2
	v_mov_b32_e32 v43, v2
	v_mov_b32_e32 v44, v2
	v_mov_b32_e32 v45, v2
	v_mov_b32_e32 v50, v2
	v_mov_b32_e32 v51, v2
	v_mov_b32_e32 v52, v2
	v_mov_b32_e32 v53, v2
	v_mov_b32_e32 v58, v2
	v_mov_b32_e32 v59, v2
	v_mov_b32_e32 v60, v2
	v_mov_b32_e32 v61, v2
	v_mov_b32_e32 v10, v2
	v_mov_b32_e32 v11, v2
	v_mov_b32_e32 v12, v2
	v_mov_b32_e32 v13, v2
	v_mov_b32_e32 v14, v2
	v_mov_b32_e32 v15, v2
	v_mov_b32_e32 v16, v2
	v_mov_b32_e32 v17, v2
	v_mov_b32_e32 v22, v2
	v_mov_b32_e32 v23, v2
	v_mov_b32_e32 v24, v2
	v_mov_b32_e32 v25, v2
	v_mov_b32_e32 v30, v2
	v_mov_b32_e32 v31, v2
	v_mov_b32_e32 v32, v2
	v_mov_b32_e32 v33, v2
	v_mov_b32_e32 v38, v2
	v_mov_b32_e32 v39, v2
	v_mov_b32_e32 v40, v2
	v_mov_b32_e32 v41, v2
	v_mov_b32_e32 v46, v2
	v_mov_b32_e32 v47, v2
	v_mov_b32_e32 v48, v2
	v_mov_b32_e32 v49, v2
	v_mov_b32_e32 v54, v2
	v_mov_b32_e32 v55, v2
	v_mov_b32_e32 v56, v2
	v_mov_b32_e32 v57, v2
	v_mov_b32_e32 v62, v2
	v_mov_b32_e32 v63, v2
	v_mov_b32_e32 v64, v2
	v_mov_b32_e32 v65, v2
	v_mov_b32_e32 v66, v2
	v_mov_b32_e32 v67, v2
	v_mov_b32_e32 v68, v2
	v_mov_b32_e32 v69, v2
	v_mov_b32_e32 v74, v2
	v_mov_b32_e32 v75, v2
	v_mov_b32_e32 v76, v2
	v_mov_b32_e32 v77, v2
	v_mov_b32_e32 v82, v2
	v_mov_b32_e32 v83, v2
	v_mov_b32_e32 v84, v2
	v_mov_b32_e32 v85, v2
	v_mov_b32_e32 v90, v2
	v_mov_b32_e32 v91, v2
	v_mov_b32_e32 v92, v2
	v_mov_b32_e32 v93, v2
	v_mov_b32_e32 v98, v2
	v_mov_b32_e32 v99, v2
	v_mov_b32_e32 v100, v2
	v_mov_b32_e32 v101, v2
	v_mov_b32_e32 v106, v2
	v_mov_b32_e32 v107, v2
	v_mov_b32_e32 v108, v2
	v_mov_b32_e32 v109, v2
	v_mov_b32_e32 v114, v2
	v_mov_b32_e32 v115, v2
	v_mov_b32_e32 v116, v2
	v_mov_b32_e32 v117, v2
	v_mov_b32_e32 v122, v2
	v_mov_b32_e32 v123, v2
	v_mov_b32_e32 v124, v2
	v_mov_b32_e32 v125, v2
	v_mov_b32_e32 v70, v2
	v_mov_b32_e32 v71, v2
	v_mov_b32_e32 v72, v2
	v_mov_b32_e32 v73, v2
	v_mov_b32_e32 v78, v2
	v_mov_b32_e32 v79, v2
	v_mov_b32_e32 v80, v2
	v_mov_b32_e32 v81, v2
	v_mov_b32_e32 v86, v2
	v_mov_b32_e32 v87, v2
	v_mov_b32_e32 v88, v2
	v_mov_b32_e32 v89, v2
	v_mov_b32_e32 v94, v2
	v_mov_b32_e32 v95, v2
	v_mov_b32_e32 v96, v2
	v_mov_b32_e32 v97, v2
	v_mov_b32_e32 v102, v2
	v_mov_b32_e32 v103, v2
	v_mov_b32_e32 v104, v2
	v_mov_b32_e32 v105, v2
	v_mov_b32_e32 v110, v2
	v_mov_b32_e32 v111, v2
	v_mov_b32_e32 v112, v2
	v_mov_b32_e32 v113, v2
	v_mov_b32_e32 v118, v2
	v_mov_b32_e32 v119, v2
	v_mov_b32_e32 v120, v2
	v_mov_b32_e32 v121, v2
	v_mov_b32_e32 v126, v2
	v_mov_b32_e32 v127, v2
	v_mov_b32_e32 v128, v2
	v_mov_b32_e32 v129, v2
	v_add_u32_e32 v238, 0x10000, v143
	v_add_u32_e32 v239, 0x14000, v143
	v_add_u32_e32 v240, 0x18000, v143
	v_add_u32_e32 v241, 0x1c000, v143
.LBB0_1490:
	s_add_u32 s22, s30, 0xfffc0080
	s_addc_u32 s23, s31, -1
	s_add_i32 s24, 0, 0x10000
	s_cmp_eq_u32 s21, 12
	s_cselect_b32 s37, s4, s23
	s_cselect_b32 s36, s5, s22
	s_cselect_b32 s35, s15, s20
	s_cselect_b32 s34, s18, s19
	s_add_i32 s25, 0, 0x14000
	ds_read_b128 v[146:149], v238
	ds_read_b128 v[150:153], v238 offset:1024
	ds_read_b128 v[154:157], v238 offset:2048
	ds_read_b128 v[158:161], v238 offset:3072
	ds_read_b128 v[162:165], v239
	ds_read_b128 v[166:169], v239 offset:1024
	ds_read_b128 v[170:173], v239 offset:2048
	ds_read_b128 v[174:177], v239 offset:3072
	s_add_i32 m0, s52, 0xc000
	ds_read_b128 v[194:197], v145
	ds_read_b128 v[198:201], v145 offset:1024
	ds_read_b128 v[202:205], v145 offset:2048
	ds_read_b128 v[206:209], v145 offset:3072
	ds_read_b128 v[222:225], v145 offset:4096
	ds_read_b128 v[226:229], v145 offset:5120
	ds_read_b128 v[230:233], v145 offset:6144
	ds_read_b128 v[234:237], v145 offset:7168
	global_load_lds_dwordx4 v136, s[30:31]
	s_add_i32 m0, s52, 0xe000
	s_nop 0
	global_load_lds_dwordx4 v138, s[30:31]
	s_waitcnt vmcnt(8)
	s_waitcnt lgkmcnt(0)
	s_barrier
; #define PG8_STAGE(bufoff, gbase, voff) do { _Pragma("unroll") for (int _i = 0; _i < 2; ++_i) \
;         __builtin_amdgcn_global_load_lds((const unsigned*)((const char*)(gbase) + (voff)[_i]), (PG8_LAS unsigned*)(lds + (bufoff) + ldsw + _i * 8192), 16, 0, 0); } while (0)
; #define PG8_LDA(dst, b, h) do { _Pragma("unroll") for (int m = 0; m < 4; ++m) _Pragma("unroll") for (int k = 0; k < 2; ++k) dst[m][k] = *(const PG8_LAS bf16x8*)(lds + PG8_SA(b, h) + aoff + m * 2048 + k * 1024); } while (0)
; #define PG8_MMA(ai, bj, At, Bt) do { __builtin_amdgcn_s_setprio(1); _Pragma("unroll") for (int m = 0; m < 4; ++m) _Pragma("unroll") for (int n = 0; n < 2; ++n) _Pragma("unroll") for (int k = 0; k < 2; ++k) \
;         acc[ai][bj][m][n] = __builtin_amdgcn_mfma_f32_16x16x32_bf16(Bt[n][k], At[m][k], acc[ai][bj][m][n], 0, 0, 0); __builtin_amdgcn_s_setprio(0); } while (0)
; #define PG8_WAIT_V(n) asm volatile("s_waitcnt vmcnt(" #n ")" ::: "memory")
; #define PG8_WAIT_L(n) asm volatile("s_waitcnt lgkmcnt(" #n ")" ::: "memory")
; #define PG8_BAR __builtin_amdgcn_s_barrier()
; #define PG8_SCHED __builtin_amdgcn_sched_barrier(0)
; template <class Epi, class Sched, bool ALIGN_EPI = false, bool SP2 = false>
; __device__ __forceinline__ void gemm_phase(PG8_LAS unsigned char* lds, const Gemm g, const Sched& S, const Epi& E) {
;     ...
;             PG8_WAIT_V(8); PG8_WAIT_L(0); PG8_BAR; PG8_MMA(0, 0, At, B0); PG8_MMA(0, 1, At, B1); PG8_BAR; PG8_SCHED;
;             PG8_LDA(At, 0, 1); PG8_STAGE(PG8_SB(0, 0), b2, voffB); PG8_STAGE(PG8_SB(0, 1), b2 + hstep, voffB); PG8_STAGE(PG8_SA(0, 0), a2, voffA);
;             PG8_WAIT_V(8); PG8_WAIT_L(0); PG8_BAR; PG8_MMA(1, 0, At, B0); PG8_MMA(1, 1, At, B1); PG8_BAR; PG8_SCHED;
	s_setprio 1
	s_waitcnt lgkmcnt(0)
	v_mfma_f32_16x16x32_bf16 v[126:129], v[146:149], v[194:197], v[126:129]
	v_mfma_f32_16x16x32_bf16 v[118:121], v[154:157], v[194:197], v[118:121]
	v_mfma_f32_16x16x32_bf16 v[110:113], v[146:149], v[202:205], v[110:113]
	v_mfma_f32_16x16x32_bf16 v[102:105], v[154:157], v[202:205], v[102:105]
	v_mfma_f32_16x16x32_bf16 v[94:97], v[146:149], v[222:225], v[94:97]
	v_mfma_f32_16x16x32_bf16 v[86:89], v[154:157], v[222:225], v[86:89]
	v_mfma_f32_16x16x32_bf16 v[78:81], v[146:149], v[230:233], v[78:81]
	v_mfma_f32_16x16x32_bf16 v[70:73], v[154:157], v[230:233], v[70:73]
	v_mfma_f32_16x16x32_bf16 v[126:129], v[150:153], v[198:201], v[126:129]
	v_mfma_f32_16x16x32_bf16 v[118:121], v[158:161], v[198:201], v[118:121]
	v_mfma_f32_16x16x32_bf16 v[110:113], v[150:153], v[206:209], v[110:113]
	v_mfma_f32_16x16x32_bf16 v[102:105], v[158:161], v[206:209], v[102:105]
	v_mfma_f32_16x16x32_bf16 v[94:97], v[150:153], v[226:229], v[94:97]
	v_mfma_f32_16x16x32_bf16 v[86:89], v[158:161], v[226:229], v[86:89]
	v_mfma_f32_16x16x32_bf16 v[78:81], v[150:153], v[234:237], v[78:81]
	v_mfma_f32_16x16x32_bf16 v[70:73], v[158:161], v[234:237], v[70:73]
	s_setprio 0
	s_setprio 1
	v_mfma_f32_16x16x32_bf16 v[122:125], v[162:165], v[194:197], v[122:125]
	v_mfma_f32_16x16x32_bf16 v[114:117], v[170:173], v[194:197], v[114:117]
	v_mfma_f32_16x16x32_bf16 v[106:109], v[162:165], v[202:205], v[106:109]
	v_mfma_f32_16x16x32_bf16 v[98:101], v[170:173], v[202:205], v[98:101]
	v_mfma_f32_16x16x32_bf16 v[90:93], v[162:165], v[222:225], v[90:93]
	v_mfma_f32_16x16x32_bf16 v[82:85], v[170:173], v[222:225], v[82:85]
	v_mfma_f32_16x16x32_bf16 v[74:77], v[162:165], v[230:233], v[74:77]
	v_mfma_f32_16x16x32_bf16 v[66:69], v[170:173], v[230:233], v[66:69]
	v_mfma_f32_16x16x32_bf16 v[122:125], v[166:169], v[198:201], v[122:125]
	v_mfma_f32_16x16x32_bf16 v[114:117], v[174:177], v[198:201], v[114:117]
	v_mfma_f32_16x16x32_bf16 v[106:109], v[166:169], v[206:209], v[106:109]
	v_mfma_f32_16x16x32_bf16 v[98:101], v[174:177], v[206:209], v[98:101]
	v_mfma_f32_16x16x32_bf16 v[90:93], v[166:169], v[226:229], v[90:93]
	v_mfma_f32_16x16x32_bf16 v[82:85], v[174:177], v[226:229], v[82:85]
	v_mfma_f32_16x16x32_bf16 v[74:77], v[166:169], v[234:237], v[74:77]
	v_mfma_f32_16x16x32_bf16 v[66:69], v[174:177], v[234:237], v[66:69]
	s_setprio 0
	s_barrier
	s_add_i32 s22, s24, s49
	s_mov_b32 m0, s22
	ds_read_b128 v[194:197], v145 offset:16384
	ds_read_b128 v[198:201], v145 offset:17408
	ds_read_b128 v[202:205], v145 offset:18432
	ds_read_b128 v[206:209], v145 offset:19456
	ds_read_b128 v[222:225], v145 offset:20480
	ds_read_b128 v[226:229], v145 offset:21504
	ds_read_b128 v[230:233], v145 offset:22528
	ds_read_b128 v[234:237], v145 offset:23552
	global_load_lds_dwordx4 v0, s[34:35]
	s_add_i32 m0, s22, 0x2000
	s_add_u32 s22, s34, 0x40000
	s_addc_u32 s23, s35, 0
	s_add_i32 s24, s25, s49
	global_load_lds_dwordx4 v130, s[34:35]
	s_mov_b32 m0, s24
	s_nop 0
	global_load_lds_dwordx4 v0, s[22:23]
	s_add_i32 m0, s24, 0x2000
	s_nop 0
	global_load_lds_dwordx4 v130, s[22:23]
	s_mov_b32 m0, s52
	s_nop 0
	global_load_lds_dwordx4 v134, s[36:37]
	s_mov_b32 m0, s53
	s_nop 0
	global_load_lds_dwordx4 v132, s[36:37]
	s_waitcnt vmcnt(8)
	s_waitcnt lgkmcnt(0)
	s_barrier
	s_setprio 1
	s_waitcnt lgkmcnt(0)
	v_mfma_f32_16x16x32_bf16 v[62:65], v[146:149], v[194:197], v[62:65]
	v_mfma_f32_16x16x32_bf16 v[54:57], v[154:157], v[194:197], v[54:57]
	v_mfma_f32_16x16x32_bf16 v[46:49], v[146:149], v[202:205], v[46:49]
	v_mfma_f32_16x16x32_bf16 v[38:41], v[154:157], v[202:205], v[38:41]
	v_mfma_f32_16x16x32_bf16 v[30:33], v[146:149], v[222:225], v[30:33]
	v_mfma_f32_16x16x32_bf16 v[22:25], v[154:157], v[222:225], v[22:25]
	v_mfma_f32_16x16x32_bf16 v[14:17], v[146:149], v[230:233], v[14:17]
	v_mfma_f32_16x16x32_bf16 v[10:13], v[154:157], v[230:233], v[10:13]
	v_mfma_f32_16x16x32_bf16 v[62:65], v[150:153], v[198:201], v[62:65]
	v_mfma_f32_16x16x32_bf16 v[54:57], v[158:161], v[198:201], v[54:57]
	v_mfma_f32_16x16x32_bf16 v[46:49], v[150:153], v[206:209], v[46:49]
	v_mfma_f32_16x16x32_bf16 v[38:41], v[158:161], v[206:209], v[38:41]
	v_mfma_f32_16x16x32_bf16 v[30:33], v[150:153], v[226:229], v[30:33]
	v_mfma_f32_16x16x32_bf16 v[22:25], v[158:161], v[226:229], v[22:25]
	v_mfma_f32_16x16x32_bf16 v[14:17], v[150:153], v[234:237], v[14:17]
	v_mfma_f32_16x16x32_bf16 v[10:13], v[158:161], v[234:237], v[10:13]
	s_setprio 0
	s_setprio 1
	v_mfma_f32_16x16x32_bf16 v[58:61], v[162:165], v[194:197], v[58:61]
	v_mfma_f32_16x16x32_bf16 v[50:53], v[170:173], v[194:197], v[50:53]
	v_mfma_f32_16x16x32_bf16 v[42:45], v[162:165], v[202:205], v[42:45]
	v_mfma_f32_16x16x32_bf16 v[34:37], v[170:173], v[202:205], v[34:37]
	v_mfma_f32_16x16x32_bf16 v[26:29], v[162:165], v[222:225], v[26:29]
	v_mfma_f32_16x16x32_bf16 v[18:21], v[170:173], v[222:225], v[18:21]
	v_mfma_f32_16x16x32_bf16 v[6:9], v[162:165], v[230:233], v[6:9]
	v_mfma_f32_16x16x32_bf16 v[2:5], v[170:173], v[230:233], v[2:5]
	v_mfma_f32_16x16x32_bf16 v[58:61], v[166:169], v[198:201], v[58:61]
	v_mfma_f32_16x16x32_bf16 v[50:53], v[174:177], v[198:201], v[50:53]
	v_mfma_f32_16x16x32_bf16 v[42:45], v[166:169], v[206:209], v[42:45]
	v_mfma_f32_16x16x32_bf16 v[34:37], v[174:177], v[206:209], v[34:37]
	v_mfma_f32_16x16x32_bf16 v[26:29], v[166:169], v[226:229], v[26:29]
	v_mfma_f32_16x16x32_bf16 v[18:21], v[174:177], v[226:229], v[18:21]
	v_mfma_f32_16x16x32_bf16 v[6:9], v[166:169], v[234:237], v[6:9]
	v_mfma_f32_16x16x32_bf16 v[2:5], v[174:177], v[234:237], v[2:5]
	s_setprio 0
	s_barrier
; #define PG8_STAGE(bufoff, gbase, voff) do { _Pragma("unroll") for (int _i = 0; _i < 2; ++_i) \
;         __builtin_amdgcn_global_load_lds((const unsigned*)((const char*)(gbase) + (voff)[_i]), (PG8_LAS unsigned*)(lds + (bufoff) + ldsw + _i * 8192), 16, 0, 0); } while (0)
; #define PG8_LDA(dst, b, h) do { _Pragma("unroll") for (int m = 0; m < 4; ++m) _Pragma("unroll") for (int k = 0; k < 2; ++k) dst[m][k] = *(const PG8_LAS bf16x8*)(lds + PG8_SA(b, h) + aoff + m * 2048 + k * 1024); } while (0)
; #define PG8_LDB(dst, b, h) do { _Pragma("unroll") for (int n = 0; n < 2; ++n) _Pragma("unroll") for (int k = 0; k < 2; ++k) dst[n][k] = *(const PG8_LAS bf16x8*)(lds + PG8_SB(b, h) + boff + n * 2048 + k * 1024); } while (0)
; template <class Epi, class Sched, bool ALIGN_EPI = false, bool SP2 = false>
; __device__ __forceinline__ void gemm_phase(PG8_LAS unsigned char* lds, const Gemm g, const Sched& S, const Epi& E) {
;     ...
;         for (int t = 0; t < nt; t += 2) {
;             const bool last = (t == nt - 2);
;             const char* a1 = cA + (size_t)(t + 1) * kstep;
;             const char* a2 = last ? nA : cA + (size_t)(t + 2) * kstep; const char* b2 = last ? nB : cB + (size_t)(t + 2) * kstep;
;             const char* a3 = a2 + kstep; const char* b3 = b2 + kstep;
;             if (last && has_next) S.a_ready(nxt);
;             if constexpr (SP2) {
;             PG8_LDB(B0, 0, 0); PG8_LDB(B1, 0, 1); PG8_SCHED; PG8_LDA(At, 0, 0); PG8_STAGE(PG8_SA(1, 1), a1 + hstep, voffA);
;             PG8_WAIT_V(8); PG8_WAIT_L(0); PG8_BAR; PG8_MMA(0, 0, At, B0); PG8_MMA(0, 1, At, B1); PG8_BAR; PG8_SCHED;
;             PG8_LDA(At, 0, 1); PG8_STAGE(PG8_SB(0, 0), b2, voffB); PG8_STAGE(PG8_SB(0, 1), b2 + hstep, voffB); PG8_STAGE(PG8_SA(0, 0), a2, voffA);
;             PG8_WAIT_V(8); PG8_WAIT_L(0); PG8_BAR; PG8_MMA(1, 0, At, B0); PG8_MMA(1, 1, At, B1); PG8_BAR; PG8_SCHED;
;             PG8_LDB(B0, 1, 0); PG8_LDB(B1, 1, 1); PG8_SCHED; PG8_LDA(At, 1, 0); PG8_STAGE(PG8_SA(0, 1), a2 + hstep, voffA);
;             PG8_WAIT_V(8); PG8_WAIT_L(0); PG8_BAR; PG8_MMA(0, 0, At, B0); PG8_MMA(0, 1, At, B1); PG8_BAR; PG8_SCHED;
;             PG8_LDA(At, 1, 1); PG8_STAGE(PG8_SB(1, 0), b3, voffB); PG8_STAGE(PG8_SB(1, 1), b3 + hstep, voffB); PG8_STAGE(PG8_SA(1, 0), a3, voffA);
;             PG8_WAIT_V(8); PG8_WAIT_L(0); PG8_BAR; PG8_MMA(1, 0, At, B0); PG8_MMA(1, 1, At, B1); PG8_BAR; PG8_SCHED;
	s_add_i32 s24, 0, 0x18000
	s_add_i32 s25, 0, 0x1c000
	ds_read_b128 v[146:149], v240
	ds_read_b128 v[150:153], v240 offset:1024
	ds_read_b128 v[154:157], v240 offset:2048
	ds_read_b128 v[158:161], v240 offset:3072
	ds_read_b128 v[162:165], v241
	ds_read_b128 v[166:169], v241 offset:1024
	ds_read_b128 v[170:173], v241 offset:2048
	ds_read_b128 v[174:177], v241 offset:3072
	s_add_u32 s22, s36, 0x40000
	s_addc_u32 s23, s37, 0
	s_mov_b32 m0, s54
	ds_read_b128 v[194:197], v145 offset:32768
	ds_read_b128 v[198:201], v145 offset:33792
	ds_read_b128 v[202:205], v145 offset:34816
	ds_read_b128 v[206:209], v145 offset:35840
	ds_read_b128 v[222:225], v145 offset:36864
	ds_read_b128 v[226:229], v145 offset:37888
	ds_read_b128 v[230:233], v145 offset:38912
	ds_read_b128 v[234:237], v145 offset:39936
	global_load_lds_dwordx4 v134, s[22:23]
	s_mov_b32 m0, s55
	s_nop 0
	global_load_lds_dwordx4 v132, s[22:23]
	s_waitcnt vmcnt(8)
	s_waitcnt lgkmcnt(0)
	s_barrier
	s_setprio 1
	s_waitcnt lgkmcnt(0)
	v_mfma_f32_16x16x32_bf16 v[126:129], v[146:149], v[194:197], v[126:129]
	v_mfma_f32_16x16x32_bf16 v[118:121], v[154:157], v[194:197], v[118:121]
	v_mfma_f32_16x16x32_bf16 v[110:113], v[146:149], v[202:205], v[110:113]
	v_mfma_f32_16x16x32_bf16 v[102:105], v[154:157], v[202:205], v[102:105]
	v_mfma_f32_16x16x32_bf16 v[94:97], v[146:149], v[222:225], v[94:97]
	v_mfma_f32_16x16x32_bf16 v[86:89], v[154:157], v[222:225], v[86:89]
	v_mfma_f32_16x16x32_bf16 v[78:81], v[146:149], v[230:233], v[78:81]
	v_mfma_f32_16x16x32_bf16 v[70:73], v[154:157], v[230:233], v[70:73]
	v_mfma_f32_16x16x32_bf16 v[126:129], v[150:153], v[198:201], v[126:129]
	v_mfma_f32_16x16x32_bf16 v[118:121], v[158:161], v[198:201], v[118:121]
	v_mfma_f32_16x16x32_bf16 v[110:113], v[150:153], v[206:209], v[110:113]
	v_mfma_f32_16x16x32_bf16 v[102:105], v[158:161], v[206:209], v[102:105]
	v_mfma_f32_16x16x32_bf16 v[94:97], v[150:153], v[226:229], v[94:97]
	v_mfma_f32_16x16x32_bf16 v[86:89], v[158:161], v[226:229], v[86:89]
	v_mfma_f32_16x16x32_bf16 v[78:81], v[150:153], v[234:237], v[78:81]
	v_mfma_f32_16x16x32_bf16 v[70:73], v[158:161], v[234:237], v[70:73]
	s_setprio 0
	s_setprio 1
	v_mfma_f32_16x16x32_bf16 v[122:125], v[162:165], v[194:197], v[122:125]
	v_mfma_f32_16x16x32_bf16 v[114:117], v[170:173], v[194:197], v[114:117]
	v_mfma_f32_16x16x32_bf16 v[106:109], v[162:165], v[202:205], v[106:109]
	v_mfma_f32_16x16x32_bf16 v[98:101], v[170:173], v[202:205], v[98:101]
	v_mfma_f32_16x16x32_bf16 v[90:93], v[162:165], v[222:225], v[90:93]
	v_mfma_f32_16x16x32_bf16 v[82:85], v[170:173], v[222:225], v[82:85]
	v_mfma_f32_16x16x32_bf16 v[74:77], v[162:165], v[230:233], v[74:77]
	v_mfma_f32_16x16x32_bf16 v[66:69], v[170:173], v[230:233], v[66:69]
	v_mfma_f32_16x16x32_bf16 v[122:125], v[166:169], v[198:201], v[122:125]
	v_mfma_f32_16x16x32_bf16 v[114:117], v[174:177], v[198:201], v[114:117]
	v_mfma_f32_16x16x32_bf16 v[106:109], v[166:169], v[206:209], v[106:109]
	v_mfma_f32_16x16x32_bf16 v[98:101], v[174:177], v[206:209], v[98:101]
	v_mfma_f32_16x16x32_bf16 v[90:93], v[166:169], v[226:229], v[90:93]
	v_mfma_f32_16x16x32_bf16 v[82:85], v[174:177], v[226:229], v[82:85]
	v_mfma_f32_16x16x32_bf16 v[74:77], v[166:169], v[234:237], v[74:77]
	v_mfma_f32_16x16x32_bf16 v[66:69], v[174:177], v[234:237], v[66:69]
	s_setprio 0
	s_barrier
	s_add_i32 s22, s24, s49
	s_add_u32 s98, s34, s28
	s_addc_u32 s99, s35, s29
	s_mov_b32 m0, s22
	ds_read_b128 v[194:197], v145 offset:49152
	ds_read_b128 v[198:201], v145 offset:50176
	ds_read_b128 v[202:205], v145 offset:51200
	ds_read_b128 v[206:209], v145 offset:52224
	ds_read_b128 v[222:225], v145 offset:53248
	ds_read_b128 v[226:229], v145 offset:54272
	ds_read_b128 v[230:233], v145 offset:55296
	ds_read_b128 v[234:237], v145 offset:56320
	global_load_lds_dwordx4 v0, s[98:99]
	s_add_i32 m0, s22, 0x2000
	s_add_u32 s22, s34, 0x40080
	s_addc_u32 s23, s35, 0
	s_add_i32 s24, s25, s49
	global_load_lds_dwordx4 v130, s[98:99]
	s_mov_b32 m0, s24
	s_nop 0
	global_load_lds_dwordx4 v0, s[22:23]
	s_add_i32 m0, s24, 0x2000
	s_nop 0
	global_load_lds_dwordx4 v130, s[22:23]
	s_add_u32 s100, s36, s28
	s_addc_u32 s101, s37, s29
	s_mov_b32 m0, s57
	s_nop 0
	global_load_lds_dwordx4 v134, s[100:101]
	s_mov_b32 m0, s58
	s_nop 0
	global_load_lds_dwordx4 v132, s[100:101]
	s_waitcnt vmcnt(8)
	s_waitcnt lgkmcnt(0)
	s_barrier
	s_setprio 1
	s_waitcnt lgkmcnt(0)
	v_mfma_f32_16x16x32_bf16 v[62:65], v[146:149], v[194:197], v[62:65]
	v_mfma_f32_16x16x32_bf16 v[54:57], v[154:157], v[194:197], v[54:57]
	v_mfma_f32_16x16x32_bf16 v[46:49], v[146:149], v[202:205], v[46:49]
	v_mfma_f32_16x16x32_bf16 v[38:41], v[154:157], v[202:205], v[38:41]
	v_mfma_f32_16x16x32_bf16 v[30:33], v[146:149], v[222:225], v[30:33]
	v_mfma_f32_16x16x32_bf16 v[22:25], v[154:157], v[222:225], v[22:25]
	v_mfma_f32_16x16x32_bf16 v[14:17], v[146:149], v[230:233], v[14:17]
	v_mfma_f32_16x16x32_bf16 v[10:13], v[154:157], v[230:233], v[10:13]
	v_mfma_f32_16x16x32_bf16 v[62:65], v[150:153], v[198:201], v[62:65]
	v_mfma_f32_16x16x32_bf16 v[54:57], v[158:161], v[198:201], v[54:57]
	v_mfma_f32_16x16x32_bf16 v[46:49], v[150:153], v[206:209], v[46:49]
	v_mfma_f32_16x16x32_bf16 v[38:41], v[158:161], v[206:209], v[38:41]
	v_mfma_f32_16x16x32_bf16 v[30:33], v[150:153], v[226:229], v[30:33]
	v_mfma_f32_16x16x32_bf16 v[22:25], v[158:161], v[226:229], v[22:25]
	v_mfma_f32_16x16x32_bf16 v[14:17], v[150:153], v[234:237], v[14:17]
	v_mfma_f32_16x16x32_bf16 v[10:13], v[158:161], v[234:237], v[10:13]
	s_setprio 0
	s_setprio 1
	v_mfma_f32_16x16x32_bf16 v[58:61], v[162:165], v[194:197], v[58:61]
	v_mfma_f32_16x16x32_bf16 v[50:53], v[170:173], v[194:197], v[50:53]
	v_mfma_f32_16x16x32_bf16 v[42:45], v[162:165], v[202:205], v[42:45]
	v_mfma_f32_16x16x32_bf16 v[34:37], v[170:173], v[202:205], v[34:37]
	v_mfma_f32_16x16x32_bf16 v[26:29], v[162:165], v[222:225], v[26:29]
	v_mfma_f32_16x16x32_bf16 v[18:21], v[170:173], v[222:225], v[18:21]
	v_mfma_f32_16x16x32_bf16 v[6:9], v[162:165], v[230:233], v[6:9]
	v_mfma_f32_16x16x32_bf16 v[2:5], v[170:173], v[230:233], v[2:5]
	v_mfma_f32_16x16x32_bf16 v[58:61], v[166:169], v[198:201], v[58:61]
	v_mfma_f32_16x16x32_bf16 v[50:53], v[174:177], v[198:201], v[50:53]
	v_mfma_f32_16x16x32_bf16 v[42:45], v[166:169], v[206:209], v[42:45]
	v_mfma_f32_16x16x32_bf16 v[34:37], v[174:177], v[206:209], v[34:37]
	v_mfma_f32_16x16x32_bf16 v[26:29], v[166:169], v[226:229], v[26:29]
	v_mfma_f32_16x16x32_bf16 v[18:21], v[174:177], v[226:229], v[18:21]
	v_mfma_f32_16x16x32_bf16 v[6:9], v[166:169], v[234:237], v[6:9]
	v_mfma_f32_16x16x32_bf16 v[2:5], v[174:177], v[234:237], v[2:5]
	s_setprio 0
	s_barrier
	s_add_i32 s21, s21, 2
	s_add_u32 s30, s30, 0x100
	s_addc_u32 s31, s31, 0
	s_add_u32 s19, s19, 0x100
	s_addc_u32 s20, s20, 0
	s_cmp_gt_u32 s21, 13
	s_cbranch_scc0 .LBB0_1490
	s_and_b64 vcc, exec, s[12:13]
	s_cbranch_vccz .LBB0_1493
	s_barrier
